# phase 0 p->bf16 conversion: loop of load-wait-convert-store iterations replaced by straight-line code (all row loads up front, counted waits)
# speedup vs baseline: 1.0025x; 1.0025x over previous
.LBB0_6:
	v_writelane_b32 v237, s10, 2
	s_or_b64 exec, exec, s[2:3]
	s_load_dwordx16 s[4:19], s[0:1], 0x0
	s_add_u32 s44, s54, 0xf340e00
	s_addc_u32 s45, s55, 0
	s_waitcnt lgkmcnt(0)
	v_writelane_b32 v237, s4, 3
	s_nop 1
	v_writelane_b32 v237, s5, 4
	v_writelane_b32 v237, s6, 5
	v_writelane_b32 v237, s7, 6
	v_writelane_b32 v237, s8, 7
	v_writelane_b32 v237, s9, 8
	v_writelane_b32 v237, s10, 9
	v_writelane_b32 v237, s11, 10
	v_writelane_b32 v237, s12, 11
	v_writelane_b32 v237, s13, 12
	v_writelane_b32 v237, s14, 13
	v_writelane_b32 v237, s15, 14
	v_writelane_b32 v237, s16, 15
	v_writelane_b32 v237, s17, 16
	v_writelane_b32 v237, s18, 17
	v_writelane_b32 v237, s19, 18
	s_load_dwordx16 s[4:19], s[0:1], 0x40
	s_waitcnt lgkmcnt(0)
	v_writelane_b32 v237, s4, 19
	s_nop 1
	v_writelane_b32 v237, s5, 20
	v_writelane_b32 v237, s6, 21
	v_writelane_b32 v237, s7, 22
	v_writelane_b32 v237, s8, 23
	v_writelane_b32 v237, s9, 24
	v_writelane_b32 v237, s10, 25
	v_writelane_b32 v237, s11, 26
	v_writelane_b32 v237, s12, 27
	v_writelane_b32 v237, s13, 28
	v_writelane_b32 v237, s14, 29
	v_writelane_b32 v237, s15, 30
	v_writelane_b32 v237, s16, 31
	v_writelane_b32 v237, s17, 32
	v_writelane_b32 v237, s18, 33
	v_writelane_b32 v237, s19, 34
	s_load_dwordx16 s[4:19], s[0:1], 0x80
	s_mov_b32 s0, 0x88000
	v_cmp_gt_i32_e32 vcc, s0, v2
	s_waitcnt lgkmcnt(0)
	v_writelane_b32 v237, s4, 35
	s_nop 1
	v_writelane_b32 v237, s5, 36
	v_writelane_b32 v237, s6, 37
	v_writelane_b32 v237, s7, 38
	v_writelane_b32 v237, s8, 39
	v_writelane_b32 v237, s9, 40
	v_writelane_b32 v237, s10, 41
	v_writelane_b32 v237, s11, 42
	v_writelane_b32 v237, s12, 43
	v_writelane_b32 v237, s13, 44
	v_writelane_b32 v237, s14, 45
	v_writelane_b32 v237, s15, 46
	v_writelane_b32 v237, s16, 47
	v_writelane_b32 v237, s17, 48
	v_writelane_b32 v237, s18, 49
	v_writelane_b32 v237, s19, 50
	s_and_saveexec_b64 s[0:1], vcc
	s_cbranch_execz .LBB0_13
	v_readlane_b32 s22, v237, 13
	v_readlane_b32 s23, v237, 14
	v_readlane_b32 s24, v237, 15
	v_readlane_b32 s25, v237, 16
	v_lshrrev_b32_e32 v6, 5, v2
	v_and_b32_e32 v3, 31, v2
	v_lshlrev_b32_e32 v4, 5, v3
	v_lshl_add_u32 v4, v6, 10, v4
	v_lshlrev_b32_e32 v5, 4, v3
	v_lshl_add_u32 v5, v6, 9, v5
	s_cmpk_lt_u32 s96, 0x80
	s_cbranch_scc0 .Lp0_ns
	global_load_dwordx4 v[72:75], v4, s[24:25]
	global_load_dwordx4 v[76:79], v4, s[24:25] offset:16
.Lp0_ns:
	v_add_u32_e32 v7, 0x400000, v4
	v_add_u32_e32 v10, 0x800000, v4
	v_add_u32_e32 v11, 0xc00000, v4
	global_load_dwordx4 v[40:43], v4, s[22:23]
	global_load_dwordx4 v[44:47], v4, s[22:23] offset:16
	global_load_dwordx4 v[48:51], v7, s[22:23]
	global_load_dwordx4 v[52:55], v7, s[22:23] offset:16
	global_load_dwordx4 v[56:59], v10, s[22:23]
	global_load_dwordx4 v[60:63], v10, s[22:23] offset:16
	global_load_dwordx4 v[64:67], v11, s[22:23]
	global_load_dwordx4 v[68:71], v11, s[22:23] offset:16
	v_add_u32_e32 v12, 0x200000, v5
	v_add_u32_e32 v13, 0x400000, v5
	v_add_u32_e32 v14, 0x600000, v5
	v_add_u32_e32 v15, 0x800000, v5
	s_waitcnt vmcnt(6)
	v_cvt_pk_bf16_f32 v20, v40, v41
	v_cvt_pk_bf16_f32 v21, v42, v43
	v_cvt_pk_bf16_f32 v22, v44, v45
	v_cvt_pk_bf16_f32 v23, v46, v47
	global_store_dwordx4 v5, v[20:23], s[44:45]
	s_waitcnt vmcnt(5)
	v_cvt_pk_bf16_f32 v24, v48, v49
	v_cvt_pk_bf16_f32 v25, v50, v51
	v_cvt_pk_bf16_f32 v26, v52, v53
	v_cvt_pk_bf16_f32 v27, v54, v55
	global_store_dwordx4 v12, v[24:27], s[44:45]
	s_waitcnt vmcnt(4)
	v_cvt_pk_bf16_f32 v28, v56, v57
	v_cvt_pk_bf16_f32 v29, v58, v59
	v_cvt_pk_bf16_f32 v30, v60, v61
	v_cvt_pk_bf16_f32 v31, v62, v63
	global_store_dwordx4 v13, v[28:31], s[44:45]
	s_waitcnt vmcnt(3)
	v_cvt_pk_bf16_f32 v32, v64, v65
	v_cvt_pk_bf16_f32 v33, v66, v67
	v_cvt_pk_bf16_f32 v34, v68, v69
	v_cvt_pk_bf16_f32 v35, v70, v71
	global_store_dwordx4 v14, v[32:35], s[44:45]
	s_cmpk_lt_u32 s96, 0x80
	s_cbranch_scc0 .Lp0_ns2
	v_cvt_pk_bf16_f32 v80, v72, v73
	v_cvt_pk_bf16_f32 v81, v74, v75
	v_cvt_pk_bf16_f32 v82, v76, v77
	v_cvt_pk_bf16_f32 v83, v78, v79
	global_store_dwordx4 v15, v[80:83], s[44:45]
.Lp0_ns2:
.LBB0_13:
	s_or_b64 exec, exec, s[0:1]
	s_cmpk_lt_i32 s96, 0x600
	s_cbranch_scc1 .LBB0_15
	s_lshl_b32 s48, s96, 2
	s_cbranch_execz .LBB0_16
	s_branch .LBB0_56
